# QK-phase packing: V-tile LDS stores + next-K loads moved into QK MFMA stream (MLA, diff); diff QK reads pipelined
# speedup vs baseline: 1.0054x; 1.0054x over previous
; #define MFMA(a, b, c) __builtin_amdgcn_mfma_f32_32x32x16_bf16((a), (b), (c), 0, 0, 0)
; DI void store_vtile(const u32x4 (&rv)[4], char* sVst) {
; #pragma unroll
;   for (int i = 0; i < 4; ++i) {
;     u32x2 lo = {rv[i][0], rv[i][1]}, hi = {rv[i][2], rv[i][3]};
;     *(u32x2*)(sVst + i * 4608) = lo;
;     *(u32x2*)(sVst + i * 4608 + 16) = hi;
;   }
; }
; DI void diff_item(const Params& p, const GroupP& g, int l_layer, int item, char* smem, bool dry) {
;     ...
;   for (int kt = 0; kt < nkt; ++kt) {
;     const bool more = kt + 1 < nkt;
;     if (more) loadK(kt + 1);
;     __builtin_amdgcn_sched_barrier(0);
;     const int key0 = kt * 64;
;     const int relmin = key0 - (qw0 + 31), relmax = key0 + 63 - qw0;
;     const bool farp = relmin >= 128, farn = relmax <= -128;
;     const float binit = (farp ? bpos : (farn ? bneg : 0.f)) - m;
;     f32x16 sa[2];
; #pragma unroll
;     for (int i = 0; i < 16; ++i) { sa[0][i] = binit; sa[1][i] = binit; }
;     {
;       const char* krd = sK + lr * 272 + map * 128 + lh * 16;
;       bf16x8 kf[4][2];
; #pragma unroll
;       for (int ks = 0; ks < 4; ++ks) {
;         kf[ks][0] = *(const bf16x8*)(krd + ks * 32);
;         kf[ks][1] = *(const bf16x8*)(krd + 32 * 272 + ks * 32);
;       }
; #pragma unroll
;       for (int ks = 0; ks < 4; ++ks) {
;         sa[0] = MFMA(kf[ks][0], qf[ks], sa[0]);
;         sa[1] = MFMA(kf[ks][1], qf[ks], sa[1]);
;       }
;     }
.LBB0_122:
	s_waitcnt vmcnt(0)
	s_add_i32 s8, s42, 2
	s_cmp_lt_i32 s8, s85
	s_cselect_b64 s[40:41], -1, 0
	s_cmp_ge_i32 s8, s85
	s_cbranch_scc1 .LBB0_124
	v_add_co_u32_e32 v64, vcc, 0x4000, v152
	s_nop 1
	v_addc_co_u32_e32 v65, vcc, 0, v153, vcc
	v_add_co_u32_e32 v66, vcc, 0x8000, v152
	s_nop 1
	v_addc_co_u32_e32 v67, vcc, 0, v153, vcc
	global_load_dwordx4 v[112:115], v[64:65], off
	global_load_dwordx4 v[136:139], v[66:67], off
	v_add_co_u32_e32 v64, vcc, 0xc000, v152
	s_nop 1
	v_addc_co_u32_e32 v65, vcc, 0, v153, vcc
	global_load_dwordx4 v[116:119], v[152:153], off
	global_load_dwordx4 v[140:143], v[64:65], off
.LBB0_124:
	s_add_i32 s10, s4, s5
	ds_read_b128 v[172:175], v159
	ds_read_b128 v[176:179], v159 offset:8704
	ds_read_b128 v[180:183], v159 offset:32
	ds_read_b128 v[188:191], v159 offset:8736
	ds_read_b128 v[192:195], v159 offset:64
	ds_read_b128 v[196:199], v159 offset:8768
	ds_read_b128 v[202:205], v159 offset:96
	ds_read_b128 v[206:209], v159 offset:8800
	ds_write2_b64 v167, v[120:121], v[122:123] offset0:128 offset1:130
	ds_write2_b64 v168, v[124:125], v[126:127] offset0:192 offset1:194
	ds_write2_b64 v169, v[128:129], v[130:131] offset1:2
	ds_write2_b64 v170, v[132:133], v[134:135] offset0:64 offset1:66
	s_add_i32 s8, s10, 33
	s_add_i32 s9, s10, 0x7f
	s_cmpk_gt_i32 s8, 0x7f
	s_cselect_b64 vcc, -1, 0
	s_cmpk_lt_i32 s9, 0xff81
	s_cselect_b64 s[8:9], -1, 0
	v_cndmask_b32_e64 v64, 0, v157, s[8:9]
	v_cndmask_b32_e32 v64, v64, v158, vcc
	v_sub_f32_e32 v64, v64, v166
	v_mov_b32_e32 v65, v64
	v_mov_b32_e32 v66, v64
	v_mov_b32_e32 v67, v64
	v_mov_b32_e32 v68, v64
	v_mov_b32_e32 v69, v64
	v_mov_b32_e32 v70, v64
	v_mov_b32_e32 v71, v64
	v_mov_b32_e32 v72, v64
	v_mov_b32_e32 v73, v64
	v_mov_b32_e32 v74, v64
	v_mov_b32_e32 v75, v64
	v_mov_b32_e32 v76, v64
	v_mov_b32_e32 v77, v64
	v_mov_b32_e32 v78, v64
	v_mov_b32_e32 v79, v64
	s_addk_i32 s10, 0xffa1
	s_cmp_lt_u32 s10, 0xfffffea3
	s_waitcnt lgkmcnt(11)
	v_mfma_f32_32x32x16_bf16 v[80:95], v[172:175], v[96:99], v[64:79]
	s_waitcnt lgkmcnt(10)
	v_mfma_f32_32x32x16_bf16 v[64:79], v[176:179], v[96:99], v[64:79]
	s_waitcnt lgkmcnt(9)
	v_mfma_f32_32x32x16_bf16 v[80:95], v[180:183], v[100:103], v[80:95]
	s_waitcnt lgkmcnt(8)
	v_mfma_f32_32x32x16_bf16 v[64:79], v[188:191], v[100:103], v[64:79]
	s_waitcnt lgkmcnt(7)
	v_mfma_f32_32x32x16_bf16 v[80:95], v[192:195], v[104:107], v[80:95]
	s_waitcnt lgkmcnt(6)
	v_mfma_f32_32x32x16_bf16 v[64:79], v[196:199], v[104:107], v[64:79]
	s_waitcnt lgkmcnt(5)
	v_mfma_f32_32x32x16_bf16 v[80:95], v[202:205], v[108:111], v[80:95]
	s_waitcnt lgkmcnt(4)
	v_mfma_f32_32x32x16_bf16 v[64:79], v[206:209], v[108:111], v[64:79]
	s_cbranch_scc1 .LBB0_126
; DI int crow(int i, int h) { return (i & 3) + 8 * (i >> 2) + 4 * h; }
; DI void diff_item(const Params& p, const GroupP& g, int l_layer, int item, char* smem, bool dry) {
;     ...
;     if (!farp && !farn) {
;       asm volatile("; near-diagonal bias tile" ::: "memory");
; #pragma unroll
;       for (int kb = 0; kb < 2; ++kb)
; #pragma unroll
;         for (int i = 0; i < 16; ++i) {
;           int rel = key0 + kb * 32 + crow(i, lh) - qpos;
;           rel = rel < -128 ? -128 : (rel > 128 ? 128 : rel);
;           sa[kb][i] += sBias[rel + 128];
;         }
;     }
	v_add_u32_e32 v184, s5, v171
	v_add_u32_e32 v172, 64, v184
	v_med3_i32 v172, v172, s84, v213
	v_lshlrev_b32_e32 v180, 2, v172
	v_add_u32_e32 v172, 0x41, v184
	v_med3_i32 v172, v172, s84, v213
	v_lshlrev_b32_e32 v181, 2, v172
	v_add_u32_e32 v172, 0x42, v184
	v_med3_i32 v172, v172, s84, v213
	v_lshlrev_b32_e32 v182, 2, v172
	v_add_u32_e32 v172, 0x43, v184
	v_med3_i32 v172, v172, s84, v213
	v_lshlrev_b32_e32 v183, 2, v172
	v_add_u32_e32 v172, 0x48, v184
	v_med3_i32 v172, v172, s84, v213
	v_lshlrev_b32_e32 v188, 2, v172
	v_add_u32_e32 v172, 0x49, v184
	v_med3_i32 v172, v172, s84, v213
	v_lshlrev_b32_e32 v189, 2, v172
	v_add_u32_e32 v172, 0x4a, v184
	v_med3_i32 v172, v172, s84, v213
	v_lshlrev_b32_e32 v190, 2, v172
	v_add_u32_e32 v172, 0x4b, v184
	v_med3_i32 v172, v172, s84, v213
	v_lshlrev_b32_e32 v191, 2, v172
	v_add_u32_e32 v172, 0x50, v184
	v_add_u32_e32 v173, 0x51, v184
	v_add_u32_e32 v174, 0x52, v184
	v_add_u32_e32 v175, 0x53, v184
	v_add_u32_e32 v176, 0x58, v184
	v_add_u32_e32 v177, 0x59, v184
	v_add_u32_e32 v178, 0x5a, v184
	v_add_u32_e32 v179, 0x5b, v184
	v_med3_i32 v172, v172, s84, v213
	v_med3_i32 v173, v173, s84, v213
	v_med3_i32 v174, v174, s84, v213
	v_med3_i32 v175, v175, s84, v213
	v_med3_i32 v176, v176, s84, v213
	v_med3_i32 v177, v177, s84, v213
	v_med3_i32 v178, v178, s84, v213
	v_med3_i32 v179, v179, s84, v213
	v_lshlrev_b32_e32 v172, 2, v172
	v_lshlrev_b32_e32 v173, 2, v173
	v_lshlrev_b32_e32 v174, 2, v174
	v_lshlrev_b32_e32 v175, 2, v175
	v_lshlrev_b32_e32 v176, 2, v176
	v_lshlrev_b32_e32 v177, 2, v177
	v_lshlrev_b32_e32 v178, 2, v178
	v_lshlrev_b32_e32 v179, 2, v179
	ds_read_b32 v172, v172 offset:36352
	ds_read_b32 v173, v173 offset:36352
	ds_read_b32 v174, v174 offset:36352
	ds_read_b32 v175, v175 offset:36352
	ds_read_b32 v176, v176 offset:36352
	ds_read_b32 v177, v177 offset:36352
	ds_read_b32 v178, v178 offset:36352
	ds_read_b32 v179, v179 offset:36352
	ds_read_b32 v180, v180 offset:36352
	ds_read_b32 v181, v181 offset:36352
	ds_read_b32 v182, v182 offset:36352
	ds_read_b32 v183, v183 offset:36352
	ds_read_b32 v188, v188 offset:36352
	ds_read_b32 v189, v189 offset:36352
	ds_read_b32 v190, v190 offset:36352
	ds_read_b32 v191, v191 offset:36352
	s_waitcnt lgkmcnt(14)
	v_pk_add_f32 v[88:89], v[88:89], v[172:173]
	v_add_u32_e32 v172, 0x60, v184
	v_med3_i32 v172, v172, s84, v213
	s_waitcnt lgkmcnt(6)
	v_pk_add_f32 v[80:81], v[80:81], v[180:181]
	v_lshlrev_b32_e32 v180, 2, v172
	v_add_u32_e32 v172, 0x61, v184
	v_med3_i32 v172, v172, s84, v213
	v_lshlrev_b32_e32 v181, 2, v172
	v_add_u32_e32 v172, 0x62, v184
	v_med3_i32 v172, v172, s84, v213
	s_waitcnt lgkmcnt(4)
	v_pk_add_f32 v[82:83], v[82:83], v[182:183]
	v_lshlrev_b32_e32 v182, 2, v172
	v_add_u32_e32 v172, 0x63, v184
	v_med3_i32 v172, v172, s84, v213
	v_lshlrev_b32_e32 v183, 2, v172
	v_add_u32_e32 v172, 0x68, v184
	v_med3_i32 v172, v172, s84, v213
	s_waitcnt lgkmcnt(2)
	v_pk_add_f32 v[84:85], v[84:85], v[188:189]
	v_lshlrev_b32_e32 v188, 2, v172
	v_add_u32_e32 v172, 0x69, v184
	v_med3_i32 v172, v172, s84, v213
	v_lshlrev_b32_e32 v189, 2, v172
	v_add_u32_e32 v172, 0x6a, v184
	v_med3_i32 v172, v172, s84, v213
	s_waitcnt lgkmcnt(0)
	v_pk_add_f32 v[86:87], v[86:87], v[190:191]
	v_lshlrev_b32_e32 v190, 2, v172
	v_add_u32_e32 v172, 0x6b, v184
	v_med3_i32 v172, v172, s84, v213
	v_pk_add_f32 v[94:95], v[94:95], v[178:179]
	v_pk_add_f32 v[92:93], v[92:93], v[176:177]
	v_pk_add_f32 v[90:91], v[90:91], v[174:175]
	v_lshlrev_b32_e32 v191, 2, v172
	v_add_u32_e32 v172, 0x70, v184
	v_add_u32_e32 v173, 0x71, v184
	v_add_u32_e32 v174, 0x72, v184
	v_add_u32_e32 v175, 0x73, v184
	v_add_u32_e32 v176, 0x78, v184
	v_add_u32_e32 v177, 0x79, v184
	v_add_u32_e32 v178, 0x7a, v184
	v_add_u32_e32 v179, 0x7b, v184
	v_med3_i32 v172, v172, s84, v213
	v_med3_i32 v173, v173, s84, v213
	v_med3_i32 v174, v174, s84, v213
	v_med3_i32 v175, v175, s84, v213
	v_med3_i32 v176, v176, s84, v213
	v_med3_i32 v177, v177, s84, v213
	v_med3_i32 v178, v178, s84, v213
	v_med3_i32 v179, v179, s84, v213
	v_lshlrev_b32_e32 v172, 2, v172
	v_lshlrev_b32_e32 v173, 2, v173
	v_lshlrev_b32_e32 v174, 2, v174
	v_lshlrev_b32_e32 v175, 2, v175
	v_lshlrev_b32_e32 v176, 2, v176
	v_lshlrev_b32_e32 v177, 2, v177
	v_lshlrev_b32_e32 v178, 2, v178
	v_lshlrev_b32_e32 v179, 2, v179
	ds_read_b32 v172, v172 offset:36352
	ds_read_b32 v173, v173 offset:36352
	ds_read_b32 v174, v174 offset:36352
	ds_read_b32 v175, v175 offset:36352
	ds_read_b32 v176, v176 offset:36352
	ds_read_b32 v177, v177 offset:36352
	ds_read_b32 v178, v178 offset:36352
	ds_read_b32 v179, v179 offset:36352
	ds_read_b32 v180, v180 offset:36352
	ds_read_b32 v181, v181 offset:36352
	ds_read_b32 v182, v182 offset:36352
	ds_read_b32 v183, v183 offset:36352
	ds_read_b32 v188, v188 offset:36352
	ds_read_b32 v189, v189 offset:36352
	ds_read_b32 v190, v190 offset:36352
	ds_read_b32 v191, v191 offset:36352
	s_waitcnt lgkmcnt(8)
	v_pk_add_f32 v[78:79], v[78:79], v[178:179]
	v_pk_add_f32 v[76:77], v[76:77], v[176:177]
	v_pk_add_f32 v[74:75], v[74:75], v[174:175]
	v_pk_add_f32 v[72:73], v[72:73], v[172:173]
	s_waitcnt lgkmcnt(0)
	v_pk_add_f32 v[70:71], v[70:71], v[190:191]
	v_pk_add_f32 v[68:69], v[68:69], v[188:189]
	v_pk_add_f32 v[66:67], v[66:67], v[182:183]
	v_pk_add_f32 v[64:65], v[64:65], v[180:181]

; #define MFMA(a, b, c) __builtin_amdgcn_mfma_f32_32x32x16_bf16((a), (b), (c), 0, 0, 0)
; DI void softmax_pv(f32x16 (&sa)[2], f32x16 (&O)[4], float& m, float& l, const char* sV, int lr, int lh, bool first) {
;     ...
;   float rsum0 = 0.f, rsum1 = 0.f;
; #pragma unroll
;   for (int i = 0; i < 16; ++i) {
;     float p0 = __builtin_amdgcn_exp2f(sa[0][i]);
;     float p1 = __builtin_amdgcn_exp2f(sa[1][i]);
;     sa[0][i] = p0;
;     sa[1][i] = p1;
;     rsum0 += p0;
;     rsum1 += p1;
;   }
;   l += rsum0 + rsum1;
;   bf16x8 pf[4];
; #pragma unroll
;   for (int g4 = 0; g4 < 4; ++g4) {
;     const int kb = g4 >> 1, s2 = g4 & 1;
;     u32x4 pp;
; #pragma unroll
;     for (int j = 0; j < 4; ++j) pp[j] = pk2(sa[kb][8 * s2 + 2 * j], sa[kb][8 * s2 + 2 * j + 1]);
;     pf[g4] = __builtin_bit_cast(bf16x8, pp);
;   }
;   const char* vrd = sV + lr * 144 + lh * 16;
;   bf16x8 vfr[4];
; #pragma unroll
;   for (int t = 0; t < 3; ++t) vfr[t] = *(const bf16x8*)(vrd + (t & 3) * (32 * 144) + (t >> 2) * 32);
;   __builtin_amdgcn_sched_group_barrier(0x100, 3, 0);
; #pragma unroll
;   for (int t = 0; t < 16; ++t) {
;     if (t + 3 < 16) {
;       vfr[(t + 3) & 3] = *(const bf16x8*)(vrd + ((t + 3) & 3) * (32 * 144) + ((t + 3) >> 2) * 32);
;       __builtin_amdgcn_sched_group_barrier(0x100, 1, 0);
;     }
;     O[t & 3] = MFMA(vfr[t & 3], pf[t >> 2], O[t & 3]);
;     __builtin_amdgcn_sched_group_barrier(0x008, 1, 0);
;   }
; DI void diff_item(const Params& p, const GroupP& g, int l_layer, int item, char* smem, bool dry) {
;     ...
;     __syncthreads();
;     if (more) { storeK(); load_vtile(rv, vbase, Lp, (kt + 1) * 64, voffV); }
;     __builtin_amdgcn_sched_barrier(0);
;     softmax_pv(sa, O, m, l, sV, lr, lh, kt == 0);
;     __syncthreads();
;     if (more) store_vtile(rv, sV_st);
;   }
.LBB0_132:
	ds_read_b128 v[192:195], v165 offset:17408
	ds_read_b128 v[196:199], v165 offset:22016
	ds_read_b128 v[202:205], v165 offset:26624
	ds_read_b128 v[206:209], v165 offset:31232
	v_exp_f32_e32 v80, v80
	v_exp_f32_e32 v81, v81
	v_exp_f32_e32 v82, v82
	v_exp_f32_e32 v83, v83
	v_exp_f32_e32 v84, v84
	v_exp_f32_e32 v85, v85
	v_exp_f32_e32 v86, v86
	v_exp_f32_e32 v87, v87
	v_cvt_pk_bf16_f32 v188, v80, v81
	v_cvt_pk_bf16_f32 v189, v82, v83
	v_cvt_pk_bf16_f32 v190, v84, v85
	v_cvt_pk_bf16_f32 v191, v86, v87
	v_exp_f32_e32 v88, v88
	v_exp_f32_e32 v89, v89
	s_waitcnt lgkmcnt(3)
	v_mfma_f32_32x32x16_bf16 v[48:63], v[192:195], v[188:191], v[48:63]
	ds_read_b128 v[192:195], v165 offset:17440
	v_exp_f32_e32 v90, v90
	v_exp_f32_e32 v91, v91
	v_exp_f32_e32 v92, v92
	v_exp_f32_e32 v93, v93
	v_exp_f32_e32 v94, v94
	v_exp_f32_e32 v95, v95
	s_waitcnt lgkmcnt(3)
	v_mfma_f32_32x32x16_bf16 v[32:47], v[196:199], v[188:191], v[32:47]
	ds_read_b128 v[196:199], v165 offset:22048
	v_exp_f32_e32 v180, v72
	v_exp_f32_e32 v181, v73
	v_exp_f32_e32 v182, v74
	v_exp_f32_e32 v183, v75
	v_cvt_pk_bf16_f32 v72, v88, v89
	v_cvt_pk_bf16_f32 v73, v90, v91
	s_waitcnt lgkmcnt(3)
	v_mfma_f32_32x32x16_bf16 v[16:31], v[202:205], v[188:191], v[16:31]
	ds_read_b128 v[202:205], v165 offset:26656
	v_cvt_pk_bf16_f32 v74, v92, v93
	v_cvt_pk_bf16_f32 v75, v94, v95
	v_exp_f32_e32 v172, v64
	v_exp_f32_e32 v173, v65
	v_exp_f32_e32 v174, v66
	v_exp_f32_e32 v175, v67
	s_waitcnt lgkmcnt(3)
	v_mfma_f32_32x32x16_bf16 v[0:15], v[206:209], v[188:191], v[0:15]
	ds_read_b128 v[188:191], v165 offset:31264
	v_exp_f32_e32 v176, v68
	v_exp_f32_e32 v177, v69
	v_exp_f32_e32 v178, v70
	v_exp_f32_e32 v179, v71
	v_cvt_pk_bf16_f32 v68, v172, v173
	v_cvt_pk_bf16_f32 v69, v174, v175
	s_waitcnt lgkmcnt(3)
	v_mfma_f32_32x32x16_bf16 v[48:63], v[192:195], v[72:75], v[48:63]
	ds_read_b128 v[192:195], v165 offset:17472
	v_cvt_pk_bf16_f32 v70, v176, v177
	v_cvt_pk_bf16_f32 v71, v178, v179
	v_exp_f32_e32 v76, v76
	v_exp_f32_e32 v77, v77
	v_exp_f32_e32 v78, v78
	v_exp_f32_e32 v79, v79
	s_waitcnt lgkmcnt(3)
	v_mfma_f32_32x32x16_bf16 v[32:47], v[196:199], v[72:75], v[32:47]
	ds_read_b128 v[196:199], v165 offset:22080
	v_cvt_pk_bf16_f32 v64, v180, v181
	v_cvt_pk_bf16_f32 v65, v182, v183
	v_cvt_pk_bf16_f32 v66, v76, v77
	v_cvt_pk_bf16_f32 v67, v78, v79
	s_and_b64 vcc, exec, s[8:9]
	s_waitcnt lgkmcnt(3)
	v_mfma_f32_32x32x16_bf16 v[16:31], v[202:205], v[72:75], v[16:31]
	ds_read_b128 v[202:205], v165 offset:26688
	s_waitcnt lgkmcnt(3)
	v_mfma_f32_32x32x16_bf16 v[0:15], v[188:191], v[72:75], v[0:15]
	ds_read_b128 v[72:75], v165 offset:31296
	s_waitcnt lgkmcnt(3)
	v_mfma_f32_32x32x16_bf16 v[48:63], v[192:195], v[68:71], v[48:63]
	ds_read_b128 v[188:191], v165 offset:17504
	s_waitcnt lgkmcnt(3)
	v_mfma_f32_32x32x16_bf16 v[32:47], v[196:199], v[68:71], v[32:47]
	ds_read_b128 v[192:195], v165 offset:22112
	s_waitcnt lgkmcnt(3)
	v_mfma_f32_32x32x16_bf16 v[16:31], v[202:205], v[68:71], v[16:31]
	ds_read_b128 v[196:199], v165 offset:26720
	s_waitcnt lgkmcnt(3)
	v_mfma_f32_32x32x16_bf16 v[0:15], v[72:75], v[68:71], v[0:15]
	ds_read_b128 v[68:71], v165 offset:31328
	s_waitcnt lgkmcnt(0)
	s_barrier
	v_mfma_f32_32x32x16_bf16 v[48:63], v[188:191], v[64:67], v[48:63]
	v_mfma_f32_32x32x16_bf16 v[32:47], v[192:195], v[64:67], v[32:47]
	v_mfma_f32_32x32x16_bf16 v[16:31], v[196:199], v[64:67], v[16:31]
	v_mfma_f32_32x32x16_bf16 v[0:15], v[68:71], v[64:67], v[0:15]
	s_branch .LBB0_121

; #define MFMA(a, b, c) __builtin_amdgcn_mfma_f32_32x32x16_bf16((a), (b), (c), 0, 0, 0)
; DI int crow(int i, int h) { return (i & 3) + 8 * (i >> 2) + 4 * h; }
; DI void store_vtile(const u32x4 (&rv)[4], char* sVst) {
; #pragma unroll
;   for (int i = 0; i < 4; ++i) {
;     u32x2 lo = {rv[i][0], rv[i][1]}, hi = {rv[i][2], rv[i][3]};
;     *(u32x2*)(sVst + i * 4608) = lo;
;     *(u32x2*)(sVst + i * 4608 + 16) = hi;
;   }
; }
; DI void mla_item(const Params& p, const GroupP& g, int item, char* smem, bool dry) {
;     ...
;   for (int kt = 0; kt < nkt; ++kt) {
;     const bool more = kt + 1 < nkt;
;     if (more) loadK(kt + 1);
;     __builtin_amdgcn_sched_barrier(0);
;     f32x16 sa[2];
; #pragma unroll
;     for (int i = 0; i < 16; ++i) { sa[0][i] = -m; sa[1][i] = -m; }
;     {
;       const char* krd = sK + lr * 400 + lh * 16;
;       bf16x8 kf[3][2];
; #pragma unroll
;       for (int q2 = 0; q2 < 2; ++q2) {
;         kf[q2][0] = *(const bf16x8*)(krd + q2 * 32);
;         kf[q2][1] = *(const bf16x8*)(krd + 32 * 400 + q2 * 32);
;       }
;       __builtin_amdgcn_sched_group_barrier(0x100, 4, 0);
; #pragma unroll
;       for (int ks = 0; ks < 12; ++ks) {
;         if (ks + 2 < 12) {
;           kf[(ks + 2) % 3][0] = *(const bf16x8*)(krd + (ks + 2) * 32);
;           kf[(ks + 2) % 3][1] = *(const bf16x8*)(krd + 32 * 400 + (ks + 2) * 32);
;           __builtin_amdgcn_sched_group_barrier(0x100, 2, 0);
;         }
;         sa[0] = MFMA(kf[ks % 3][0], qf[ks], sa[0]);
;         sa[1] = MFMA(kf[ks % 3][1], qf[ks], sa[1]);
;         __builtin_amdgcn_sched_group_barrier(0x008, 2, 0);
;       }
;     }
;     if (kt == nkt - 1) {
;       asm volatile("; masked tail tile" ::: "memory");
; #pragma unroll
;       for (int kb = 0; kb < 2; ++kb)
; #pragma unroll
;         for (int i = 0; i < 16; ++i)
;           if (kt * 64 + kb * 32 + crow(i, lh) >= L) sa[kb][i] = -1e30f;
;     }
.LBB0_154:
	s_waitcnt vmcnt(0)
	v_add_u32_e32 v184, v223, v192
	ds_read_b128 v[202:205], v184
	ds_read_b128 v[206:209], v184 offset:12800
	v_xor_b32_e32 v64, 0x80000000, v226
	v_mov_b32_e32 v65, v64
	v_mov_b32_e32 v66, v64
	v_mov_b32_e32 v67, v64
	v_mov_b32_e32 v68, v64
	v_mov_b32_e32 v69, v64
	v_mov_b32_e32 v70, v64
	v_mov_b32_e32 v71, v64
	v_mov_b32_e32 v72, v64
	v_mov_b32_e32 v73, v64
	v_mov_b32_e32 v74, v64
	v_mov_b32_e32 v75, v64
	v_mov_b32_e32 v76, v64
	v_mov_b32_e32 v77, v64
	v_mov_b32_e32 v78, v64
	v_mov_b32_e32 v79, v64
	ds_read_b128 v[232:235], v184 offset:32
	ds_read_b128 v[236:239], v184 offset:12832
	ds_read_b128 v[240:243], v184 offset:64
	ds_read_b128 v[244:247], v184 offset:12864
	s_waitcnt lgkmcnt(5)
	v_mfma_f32_32x32x16_bf16 v[80:95], v[202:205], v[96:99], v[64:79]
	s_waitcnt lgkmcnt(4)
	v_mfma_f32_32x32x16_bf16 v[64:79], v[206:209], v[96:99], v[64:79]
	ds_read_b128 v[202:205], v184 offset:96
	ds_read_b128 v[206:209], v184 offset:12896
	s_cmp_ge_i32 s92, s85
	s_cbranch_scc1 .Lqk0_nokld
	global_load_dwordx4 v[144:147], v[198:199], off
	v_add_co_u32_e32 v148, vcc, 0x8000, v198
	s_nop 1
	v_addc_co_u32_e32 v149, vcc, 0, v199, vcc
	v_add_co_u32_e32 v160, vcc, 0x10000, v198
	s_nop 1
	v_addc_co_u32_e32 v161, vcc, 0, v199, vcc
	global_load_dwordx4 v[148:151], v[148:149], off
	v_add_co_u32_e32 v172, vcc, 0x18000, v198
	s_nop 1
	v_addc_co_u32_e32 v173, vcc, 0, v199, vcc
	global_load_dwordx4 v[160:163], v[160:161], off
	global_load_dwordx4 v[172:175], v[172:173], off
	v_add_co_u32_e32 v180, vcc, 0x1000, v196
	s_nop 1
	v_addc_co_u32_e32 v181, vcc, 0, v197, vcc
	global_load_dwordx4 v[176:179], v[196:197], off
	global_load_dwordx4 v[180:183], v[180:181], off
.Lqk0_nokld:
	s_waitcnt lgkmcnt(5)
	v_mfma_f32_32x32x16_bf16 v[80:95], v[232:235], v[100:103], v[80:95]
	s_waitcnt lgkmcnt(4)
	v_mfma_f32_32x32x16_bf16 v[64:79], v[236:239], v[100:103], v[64:79]
	ds_read_b128 v[232:235], v184 offset:128
	ds_read_b128 v[236:239], v184 offset:12928
	s_waitcnt lgkmcnt(5)
	v_mfma_f32_32x32x16_bf16 v[80:95], v[240:243], v[104:107], v[80:95]
	s_waitcnt lgkmcnt(4)
	v_mfma_f32_32x32x16_bf16 v[64:79], v[244:247], v[104:107], v[64:79]
	ds_read_b128 v[240:243], v184 offset:160
	ds_read_b128 v[244:247], v184 offset:12960
	s_waitcnt lgkmcnt(5)
	v_mfma_f32_32x32x16_bf16 v[80:95], v[202:205], v[108:111], v[80:95]
	s_waitcnt lgkmcnt(4)
	v_mfma_f32_32x32x16_bf16 v[64:79], v[206:209], v[108:111], v[64:79]
	ds_read_b128 v[202:205], v184 offset:192
	ds_read_b128 v[206:209], v184 offset:12992
	ds_write2_b64 v227, v[152:153], v[154:155] offset0:128 offset1:130
	s_waitcnt lgkmcnt(6)
	v_mfma_f32_32x32x16_bf16 v[80:95], v[232:235], v[112:115], v[80:95]
	s_waitcnt lgkmcnt(5)
	v_mfma_f32_32x32x16_bf16 v[64:79], v[236:239], v[112:115], v[64:79]
	ds_read_b128 v[232:235], v184 offset:224
	ds_read_b128 v[236:239], v184 offset:13024
	ds_write2_b64 v228, v[156:157], v[158:159] offset0:192 offset1:194
	s_waitcnt lgkmcnt(7)
	v_mfma_f32_32x32x16_bf16 v[80:95], v[240:243], v[116:119], v[80:95]
	s_waitcnt lgkmcnt(6)
	v_mfma_f32_32x32x16_bf16 v[64:79], v[244:247], v[116:119], v[64:79]
	ds_read_b128 v[240:243], v184 offset:256
	ds_read_b128 v[244:247], v184 offset:13056
	ds_write2_b64 v229, v[164:165], v[166:167] offset1:2
	s_waitcnt lgkmcnt(8)
	v_mfma_f32_32x32x16_bf16 v[80:95], v[202:205], v[120:123], v[80:95]
	s_waitcnt lgkmcnt(7)
	v_mfma_f32_32x32x16_bf16 v[64:79], v[206:209], v[120:123], v[64:79]
	ds_read_b128 v[202:205], v184 offset:288
	ds_read_b128 v[206:209], v184 offset:13088
	ds_write2_b64 v230, v[168:169], v[170:171] offset0:64 offset1:66
	s_waitcnt lgkmcnt(8)
	v_mfma_f32_32x32x16_bf16 v[80:95], v[232:235], v[124:127], v[80:95]
	s_waitcnt lgkmcnt(7)
	v_mfma_f32_32x32x16_bf16 v[64:79], v[236:239], v[124:127], v[64:79]
	ds_read_b128 v[232:235], v184 offset:320
	ds_read_b128 v[236:239], v184 offset:13120
	s_waitcnt lgkmcnt(7)
	v_mfma_f32_32x32x16_bf16 v[80:95], v[240:243], v[128:131], v[80:95]
	s_waitcnt lgkmcnt(6)
	v_mfma_f32_32x32x16_bf16 v[64:79], v[244:247], v[128:131], v[64:79]
	ds_read_b128 v[240:243], v184 offset:352
	ds_read_b128 v[244:247], v184 offset:13152
	s_waitcnt lgkmcnt(6)
	v_mfma_f32_32x32x16_bf16 v[80:95], v[202:205], v[132:135], v[80:95]
	s_waitcnt lgkmcnt(5)
	v_mfma_f32_32x32x16_bf16 v[64:79], v[206:209], v[132:135], v[64:79]
	s_waitcnt lgkmcnt(3)
	v_mfma_f32_32x32x16_bf16 v[80:95], v[232:235], v[136:139], v[80:95]
	s_waitcnt lgkmcnt(2)
	v_mfma_f32_32x32x16_bf16 v[64:79], v[236:239], v[136:139], v[64:79]
	s_waitcnt lgkmcnt(1)
	v_mfma_f32_32x32x16_bf16 v[80:95], v[240:243], v[140:143], v[80:95]
	s_waitcnt lgkmcnt(0)
	v_mfma_f32_32x32x16_bf16 v[64:79], v[244:247], v[140:143], v[64:79]
	s_cmp_lg_u32 s85, s92
	s_cbranch_scc1 .LBB0_156
	s_nop 8
	v_cndmask_b32_e64 v95, v214, v95, s[8:9]
	v_cndmask_b32_e64 v94, v214, v94, s[12:13]
	v_cndmask_b32_e64 v93, v214, v93, s[14:15]
	v_cndmask_b32_e64 v92, v214, v92, s[16:17]
	v_cndmask_b32_e64 v91, v214, v91, s[18:19]
	v_cndmask_b32_e64 v90, v214, v90, s[20:21]
	v_cndmask_b32_e64 v89, v214, v89, s[22:23]
	v_cndmask_b32_e64 v88, v214, v88, s[24:25]
	v_cndmask_b32_e64 v87, v214, v87, s[26:27]
	v_cndmask_b32_e64 v86, v214, v86, s[28:29]
	v_cndmask_b32_e64 v85, v214, v85, s[30:31]
	v_cndmask_b32_e64 v84, v214, v84, s[34:35]
	v_cndmask_b32_e64 v83, v214, v83, s[36:37]
	v_cndmask_b32_e64 v82, v214, v82, s[38:39]
	v_cndmask_b32_e64 v81, v214, v81, s[40:41]
	v_cndmask_b32_e64 v80, v214, v80, s[42:43]
	v_cndmask_b32_e64 v79, v214, v79, s[10:11]
	v_cndmask_b32_e64 v78, v214, v78, s[44:45]
	v_cndmask_b32_e64 v77, v214, v77, s[46:47]
	v_cndmask_b32_e64 v76, v214, v76, s[48:49]
	v_cndmask_b32_e64 v75, v214, v75, s[50:51]
	v_cndmask_b32_e64 v74, v214, v74, s[52:53]
	v_cndmask_b32_e64 v73, v214, v73, s[54:55]
	v_cndmask_b32_e64 v72, v214, v72, s[56:57]
	v_cndmask_b32_e64 v71, v214, v71, s[58:59]
	v_cndmask_b32_e64 v70, v214, v70, s[60:61]
	v_cndmask_b32_e64 v69, v214, v69, s[62:63]
	v_cndmask_b32_e64 v68, v214, v68, s[64:65]
	v_cndmask_b32_e64 v67, v214, v67, s[66:67]
	v_cndmask_b32_e64 v66, v214, v66, s[68:69]
	v_cndmask_b32_e64 v65, v214, v65, s[70:71]
	v_cndmask_b32_e64 v64, v214, v64, s[72:73]

; #define MFMA(a, b, c) __builtin_amdgcn_mfma_f32_32x32x16_bf16((a), (b), (c), 0, 0, 0)
; DI void softmax_pv(f32x16 (&sa)[2], f32x16 (&O)[4], float& m, float& l, const char* sV, int lr, int lh, bool first) {
;     ...
;   float rsum0 = 0.f, rsum1 = 0.f;
; #pragma unroll
;   for (int i = 0; i < 16; ++i) {
;     float p0 = __builtin_amdgcn_exp2f(sa[0][i]);
;     float p1 = __builtin_amdgcn_exp2f(sa[1][i]);
;     sa[0][i] = p0;
;     sa[1][i] = p1;
;     rsum0 += p0;
;     rsum1 += p1;
;   }
;   l += rsum0 + rsum1;
;   bf16x8 pf[4];
; #pragma unroll
;   for (int g4 = 0; g4 < 4; ++g4) {
;     const int kb = g4 >> 1, s2 = g4 & 1;
;     u32x4 pp;
; #pragma unroll
;     for (int j = 0; j < 4; ++j) pp[j] = pk2(sa[kb][8 * s2 + 2 * j], sa[kb][8 * s2 + 2 * j + 1]);
;     pf[g4] = __builtin_bit_cast(bf16x8, pp);
;   }
;   const char* vrd = sV + lr * 144 + lh * 16;
;   bf16x8 vfr[4];
; #pragma unroll
;   for (int t = 0; t < 3; ++t) vfr[t] = *(const bf16x8*)(vrd + (t & 3) * (32 * 144) + (t >> 2) * 32);
;   __builtin_amdgcn_sched_group_barrier(0x100, 3, 0);
; #pragma unroll
;   for (int t = 0; t < 16; ++t) {
;     if (t + 3 < 16) {
;       vfr[(t + 3) & 3] = *(const bf16x8*)(vrd + ((t + 3) & 3) * (32 * 144) + ((t + 3) >> 2) * 32);
;       __builtin_amdgcn_sched_group_barrier(0x100, 1, 0);
;     }
;     O[t & 3] = MFMA(vfr[t & 3], pf[t >> 2], O[t & 3]);
;     __builtin_amdgcn_sched_group_barrier(0x008, 1, 0);
;   }
; DI void mla_item(const Params& p, const GroupP& g, int item, char* smem, bool dry) {
;     ...
;     softmax_pv(sa, O, m, l, sV, lr, lh, kt == 0);
;     __syncthreads();
;     if (more) store_vtile(rv, sV_st);
;   }
.LBB0_160:
	ds_read_b128 v[202:205], v225 offset:25600
	ds_read_b128 v[232:235], v225 offset:30208
	ds_read_b128 v[236:239], v225 offset:34816
	ds_read_b128 v[240:243], v225 offset:39424
	v_exp_f32_e32 v80, v80
	v_exp_f32_e32 v81, v81
	v_exp_f32_e32 v82, v82
	v_exp_f32_e32 v83, v83
	v_exp_f32_e32 v84, v84
	v_exp_f32_e32 v85, v85
	v_exp_f32_e32 v86, v86
	v_exp_f32_e32 v87, v87
	v_cvt_pk_bf16_f32 v206, v80, v81
	v_cvt_pk_bf16_f32 v207, v82, v83
	v_cvt_pk_bf16_f32 v208, v84, v85
	v_cvt_pk_bf16_f32 v209, v86, v87
	v_exp_f32_e32 v231, v89
	v_exp_f32_e32 v184, v90
	s_waitcnt lgkmcnt(3)
	v_mfma_f32_32x32x16_bf16 v[48:63], v[202:205], v[206:209], v[48:63]
	ds_read_b128 v[202:205], v225 offset:25632
	v_exp_f32_e32 v90, v91
	v_exp_f32_e32 v89, v92
	v_exp_f32_e32 v92, v94
	v_exp_f32_e32 v91, v95
	v_exp_f32_e32 v95, v64
	v_exp_f32_e32 v94, v65
	s_waitcnt lgkmcnt(3)
	v_mfma_f32_32x32x16_bf16 v[32:47], v[232:235], v[206:209], v[32:47]
	ds_read_b128 v[244:247], v225 offset:30240
	v_exp_f32_e32 v232, v88
	v_exp_f32_e32 v88, v93
	v_exp_f32_e32 v93, v66
	v_exp_f32_e32 v66, v67
	v_exp_f32_e32 v65, v68
	v_exp_f32_e32 v64, v69
	s_waitcnt lgkmcnt(3)
	v_mfma_f32_32x32x16_bf16 v[16:31], v[236:239], v[206:209], v[16:31]
	ds_read_b128 v[234:237], v225 offset:34848
	v_exp_f32_e32 v68, v70
	v_exp_f32_e32 v67, v71
	v_exp_f32_e32 v233, v73
	v_exp_f32_e32 v71, v75
	v_exp_f32_e32 v70, v76
	v_exp_f32_e32 v69, v77
	s_waitcnt lgkmcnt(3)
	v_mfma_f32_32x32x16_bf16 v[0:15], v[240:243], v[206:209], v[0:15]
	ds_read_b128 v[238:241], v225 offset:39456
	v_cvt_pk_bf16_f32 v206, v232, v231
	v_cvt_pk_bf16_f32 v207, v184, v90
	v_cvt_pk_bf16_f32 v208, v89, v88
	v_cvt_pk_bf16_f32 v209, v92, v91
	v_exp_f32_e32 v73, v79
	s_and_b64 vcc, exec, s[74:75]
	s_waitcnt lgkmcnt(3)
	v_mfma_f32_32x32x16_bf16 v[48:63], v[202:205], v[206:209], v[48:63]
	ds_read_b128 v[202:205], v225 offset:25664
	s_waitcnt lgkmcnt(3)
	v_mfma_f32_32x32x16_bf16 v[32:47], v[244:247], v[206:209], v[32:47]
	ds_read_b128 v[242:245], v225 offset:30272
	s_waitcnt lgkmcnt(3)
	v_mfma_f32_32x32x16_bf16 v[16:31], v[234:237], v[206:209], v[16:31]
	ds_read_b128 v[234:237], v225 offset:34880
	s_waitcnt lgkmcnt(3)
	v_mfma_f32_32x32x16_bf16 v[0:15], v[238:241], v[206:209], v[0:15]
	ds_read_b128 v[238:241], v225 offset:39488
	v_cvt_pk_bf16_f32 v206, v95, v94
	v_cvt_pk_bf16_f32 v207, v93, v66
	v_cvt_pk_bf16_f32 v208, v65, v64
	v_cvt_pk_bf16_f32 v209, v68, v67
	s_waitcnt lgkmcnt(3)
	s_nop 0
	v_mfma_f32_32x32x16_bf16 v[48:63], v[202:205], v[206:209], v[48:63]
	ds_read_b128 v[202:205], v225 offset:25696
	s_waitcnt lgkmcnt(3)
	v_mfma_f32_32x32x16_bf16 v[32:47], v[242:245], v[206:209], v[32:47]
	ds_read_b128 v[242:245], v225 offset:30304
	s_waitcnt lgkmcnt(3)
	v_mfma_f32_32x32x16_bf16 v[16:31], v[234:237], v[206:209], v[16:31]
	ds_read_b128 v[246:249], v225 offset:34912
	v_exp_f32_e32 v234, v72
	v_exp_f32_e32 v72, v74
	v_exp_f32_e32 v74, v78
	v_cvt_pk_bf16_f32 v78, v70, v69
	v_cvt_pk_bf16_f32 v76, v234, v233
	v_cvt_pk_bf16_f32 v77, v72, v71
	s_waitcnt lgkmcnt(3)
	v_mfma_f32_32x32x16_bf16 v[0:15], v[238:241], v[206:209], v[0:15]
	ds_read_b128 v[206:209], v225 offset:39520
	v_cvt_pk_bf16_f32 v79, v74, v73
	s_waitcnt lgkmcnt(0)
	s_barrier
	v_mfma_f32_32x32x16_bf16 v[48:63], v[202:205], v[76:79], v[48:63]
	v_mfma_f32_32x32x16_bf16 v[32:47], v[242:245], v[76:79], v[32:47]
	v_mfma_f32_32x32x16_bf16 v[16:31], v[246:249], v[76:79], v[16:31]
	v_mfma_f32_32x32x16_bf16 v[0:15], v[206:209], v[76:79], v[0:15]
	s_branch .LBB0_151

; DI void diff_item(const Params& p, const GroupP& g, int l_layer, int item, char* smem, bool dry) {
;     ...
;   auto loadK = [&](int kt) {
;     const char* u1 = (const char*)kd + (long)kt * (64 * 1024);
; #pragma unroll
;     for (int i = 0; i < 4; ++i) rk[i] = *(const u32x4*)(u1 + i * (16 * 1024) + voffK);
;   };
;     ...
;   for (int kt = 0; kt < nkt; ++kt) {
;     const bool more = kt + 1 < nkt;
;     if (more) loadK(kt + 1);
;     __builtin_amdgcn_sched_barrier(0);
;     const int key0 = kt * 64;
;     const int relmin = key0 - (qw0 + 31), relmax = key0 + 63 - qw0;
;     const bool farp = relmin >= 128, farn = relmax <= -128;
;     const float binit = (farp ? bpos : (farn ? bneg : 0.f)) - m;
.LBB0_194:
	s_waitcnt vmcnt(0)
	s_add_i32 s8, s42, 2
	s_cmp_lt_i32 s8, s33
	s_cselect_b64 s[40:41], -1, 0
	s_cmp_ge_i32 s8, s33
	s_cbranch_scc1 .LBB0_196
	v_add_co_u32_e32 v64, vcc, 0x4000, v152
	s_nop 1
	v_addc_co_u32_e32 v65, vcc, 0, v153, vcc
	v_add_co_u32_e32 v66, vcc, 0x8000, v152
	s_nop 1
	v_addc_co_u32_e32 v67, vcc, 0, v153, vcc
	global_load_dwordx4 v[112:115], v[64:65], off
	global_load_dwordx4 v[136:139], v[66:67], off
	v_add_co_u32_e32 v64, vcc, 0xc000, v152
	s_nop 1
	v_addc_co_u32_e32 v65, vcc, 0, v153, vcc
	global_load_dwordx4 v[116:119], v[152:153], off
	global_load_dwordx4 v[140:143], v[64:65], off

; #define MFMA(a, b, c) __builtin_amdgcn_mfma_f32_32x32x16_bf16((a), (b), (c), 0, 0, 0)
; DI int crow(int i, int h) { return (i & 3) + 8 * (i >> 2) + 4 * h; }
; DI void store_vtile(const u32x4 (&rv)[4], char* sVst) {
; #pragma unroll
;   for (int i = 0; i < 4; ++i) {
;     u32x2 lo = {rv[i][0], rv[i][1]}, hi = {rv[i][2], rv[i][3]};
;     *(u32x2*)(sVst + i * 4608) = lo;
;     *(u32x2*)(sVst + i * 4608 + 16) = hi;
;   }
; }
; DI void mla_item(const Params& p, const GroupP& g, int item, char* smem, bool dry) {
;     ...
;   for (int kt = 0; kt < nkt; ++kt) {
;     const bool more = kt + 1 < nkt;
;     if (more) loadK(kt + 1);
;     __builtin_amdgcn_sched_barrier(0);
;     f32x16 sa[2];
; #pragma unroll
;     for (int i = 0; i < 16; ++i) { sa[0][i] = -m; sa[1][i] = -m; }
;     {
;       const char* krd = sK + lr * 400 + lh * 16;
;       bf16x8 kf[3][2];
; #pragma unroll
;       for (int q2 = 0; q2 < 2; ++q2) {
;         kf[q2][0] = *(const bf16x8*)(krd + q2 * 32);
;         kf[q2][1] = *(const bf16x8*)(krd + 32 * 400 + q2 * 32);
;       }
;       __builtin_amdgcn_sched_group_barrier(0x100, 4, 0);
; #pragma unroll
;       for (int ks = 0; ks < 12; ++ks) {
;         if (ks + 2 < 12) {
;           kf[(ks + 2) % 3][0] = *(const bf16x8*)(krd + (ks + 2) * 32);
;           kf[(ks + 2) % 3][1] = *(const bf16x8*)(krd + 32 * 400 + (ks + 2) * 32);
;           __builtin_amdgcn_sched_group_barrier(0x100, 2, 0);
;         }
;         sa[0] = MFMA(kf[ks % 3][0], qf[ks], sa[0]);
;         sa[1] = MFMA(kf[ks % 3][1], qf[ks], sa[1]);
;         __builtin_amdgcn_sched_group_barrier(0x008, 2, 0);
;       }
;     }
;     if (kt == nkt - 1) {
;       asm volatile("; masked tail tile" ::: "memory");
; #pragma unroll
;       for (int kb = 0; kb < 2; ++kb)
; #pragma unroll
;         for (int i = 0; i < 16; ++i)
;           if (kt * 64 + kb * 32 + crow(i, lh) >= L) sa[kb][i] = -1e30f;
;     }
.LBB0_227:
	s_waitcnt vmcnt(0)
	v_add_u32_e32 v184, v223, v192
	ds_read_b128 v[232:235], v184
	ds_read_b128 v[236:239], v184 offset:12800
	v_xor_b32_e32 v64, 0x80000000, v226
	v_mov_b32_e32 v65, v64
	v_mov_b32_e32 v66, v64
	v_mov_b32_e32 v67, v64
	v_mov_b32_e32 v68, v64
	v_mov_b32_e32 v69, v64
	v_mov_b32_e32 v70, v64
	v_mov_b32_e32 v71, v64
	v_mov_b32_e32 v72, v64
	v_mov_b32_e32 v73, v64
	v_mov_b32_e32 v74, v64
	v_mov_b32_e32 v75, v64
	v_mov_b32_e32 v76, v64
	v_mov_b32_e32 v77, v64
	v_mov_b32_e32 v78, v64
	v_mov_b32_e32 v79, v64
	ds_read_b128 v[240:243], v184 offset:32
	ds_read_b128 v[244:247], v184 offset:12832
	ds_read_b128 v[248:251], v184 offset:64
	ds_read_b128 v[206:209], v184 offset:12864
	s_waitcnt lgkmcnt(5)
	v_mfma_f32_32x32x16_bf16 v[80:95], v[232:235], v[96:99], v[64:79]
	s_waitcnt lgkmcnt(4)
	v_mfma_f32_32x32x16_bf16 v[64:79], v[236:239], v[96:99], v[64:79]
	ds_read_b128 v[232:235], v184 offset:96
	ds_read_b128 v[236:239], v184 offset:12896
	s_cmp_ge_i32 s92, s33
	s_cbranch_scc1 .Lqk1_nokld
	global_load_dwordx4 v[144:147], v[198:199], off
	v_add_co_u32_e32 v148, vcc, 0x8000, v198
	s_nop 1
	v_addc_co_u32_e32 v149, vcc, 0, v199, vcc
	v_add_co_u32_e32 v160, vcc, 0x10000, v198
	s_nop 1
	v_addc_co_u32_e32 v161, vcc, 0, v199, vcc
	global_load_dwordx4 v[148:151], v[148:149], off
	v_add_co_u32_e32 v172, vcc, 0x18000, v198
	s_nop 1
	v_addc_co_u32_e32 v173, vcc, 0, v199, vcc
	global_load_dwordx4 v[160:163], v[160:161], off
	global_load_dwordx4 v[172:175], v[172:173], off
	v_add_co_u32_e32 v180, vcc, 0x1000, v196
	s_nop 1
	v_addc_co_u32_e32 v181, vcc, 0, v197, vcc
	global_load_dwordx4 v[176:179], v[196:197], off
	global_load_dwordx4 v[180:183], v[180:181], off
.Lqk1_nokld:
	s_waitcnt lgkmcnt(5)
	v_mfma_f32_32x32x16_bf16 v[80:95], v[240:243], v[100:103], v[80:95]
	s_waitcnt lgkmcnt(4)
	v_mfma_f32_32x32x16_bf16 v[64:79], v[244:247], v[100:103], v[64:79]
	ds_read_b128 v[240:243], v184 offset:128
	ds_read_b128 v[244:247], v184 offset:12928
	s_waitcnt lgkmcnt(5)
	v_mfma_f32_32x32x16_bf16 v[80:95], v[248:251], v[104:107], v[80:95]
	s_waitcnt lgkmcnt(4)
	v_mfma_f32_32x32x16_bf16 v[64:79], v[206:209], v[104:107], v[64:79]
	ds_read_b128 v[206:209], v184 offset:160
	ds_read_b128 v[248:251], v184 offset:12960
	s_waitcnt lgkmcnt(5)
	v_mfma_f32_32x32x16_bf16 v[80:95], v[232:235], v[108:111], v[80:95]
	s_waitcnt lgkmcnt(4)
	v_mfma_f32_32x32x16_bf16 v[64:79], v[236:239], v[108:111], v[64:79]
	ds_read_b128 v[232:235], v184 offset:192
	ds_read_b128 v[236:239], v184 offset:12992
	ds_write2_b64 v227, v[152:153], v[154:155] offset0:128 offset1:130
	s_waitcnt lgkmcnt(6)
	v_mfma_f32_32x32x16_bf16 v[80:95], v[240:243], v[112:115], v[80:95]
	s_waitcnt lgkmcnt(5)
	v_mfma_f32_32x32x16_bf16 v[64:79], v[244:247], v[112:115], v[64:79]
	ds_read_b128 v[240:243], v184 offset:224
	ds_read_b128 v[244:247], v184 offset:13024
	ds_write2_b64 v228, v[156:157], v[158:159] offset0:192 offset1:194
	s_waitcnt lgkmcnt(7)
	v_mfma_f32_32x32x16_bf16 v[80:95], v[206:209], v[116:119], v[80:95]
	s_waitcnt lgkmcnt(6)
	v_mfma_f32_32x32x16_bf16 v[64:79], v[248:251], v[116:119], v[64:79]
	ds_read_b128 v[206:209], v184 offset:256
	ds_read_b128 v[248:251], v184 offset:13056
	ds_write2_b64 v229, v[164:165], v[166:167] offset1:2
	s_waitcnt lgkmcnt(8)
	v_mfma_f32_32x32x16_bf16 v[80:95], v[232:235], v[120:123], v[80:95]
	s_waitcnt lgkmcnt(7)
	v_mfma_f32_32x32x16_bf16 v[64:79], v[236:239], v[120:123], v[64:79]
	ds_read_b128 v[232:235], v184 offset:288
	ds_read_b128 v[236:239], v184 offset:13088
	ds_write2_b64 v230, v[168:169], v[170:171] offset0:64 offset1:66
	s_waitcnt lgkmcnt(8)
	v_mfma_f32_32x32x16_bf16 v[80:95], v[240:243], v[124:127], v[80:95]
	s_waitcnt lgkmcnt(7)
	v_mfma_f32_32x32x16_bf16 v[64:79], v[244:247], v[124:127], v[64:79]
	ds_read_b128 v[240:243], v184 offset:320
	ds_read_b128 v[244:247], v184 offset:13120
	s_waitcnt lgkmcnt(7)
	v_mfma_f32_32x32x16_bf16 v[80:95], v[206:209], v[128:131], v[80:95]
	s_waitcnt lgkmcnt(6)
	v_mfma_f32_32x32x16_bf16 v[64:79], v[248:251], v[128:131], v[64:79]
	ds_read_b128 v[206:209], v184 offset:352
	ds_read_b128 v[248:251], v184 offset:13152
	s_waitcnt lgkmcnt(6)
	v_mfma_f32_32x32x16_bf16 v[80:95], v[232:235], v[132:135], v[80:95]
	s_waitcnt lgkmcnt(5)
	v_mfma_f32_32x32x16_bf16 v[64:79], v[236:239], v[132:135], v[64:79]
	s_waitcnt lgkmcnt(3)
	v_mfma_f32_32x32x16_bf16 v[80:95], v[240:243], v[136:139], v[80:95]
	s_waitcnt lgkmcnt(2)
	v_mfma_f32_32x32x16_bf16 v[64:79], v[244:247], v[136:139], v[64:79]
	s_waitcnt lgkmcnt(1)
	v_mfma_f32_32x32x16_bf16 v[80:95], v[206:209], v[140:143], v[80:95]
	s_waitcnt lgkmcnt(0)
	v_mfma_f32_32x32x16_bf16 v[64:79], v[248:251], v[140:143], v[64:79]
	s_cmp_lg_u32 s33, s92
	s_cbranch_scc1 .LBB0_229
	s_nop 8
	v_cndmask_b32_e64 v95, v214, v95, s[8:9]
	v_cndmask_b32_e64 v94, v214, v94, s[12:13]
	v_cndmask_b32_e64 v93, v214, v93, s[14:15]
	v_cndmask_b32_e64 v92, v214, v92, s[16:17]
	v_cndmask_b32_e64 v91, v214, v91, s[18:19]
	v_cndmask_b32_e64 v90, v214, v90, s[20:21]
	v_cndmask_b32_e64 v89, v214, v89, s[22:23]
	v_cndmask_b32_e64 v88, v214, v88, s[24:25]
	v_cndmask_b32_e64 v87, v214, v87, s[26:27]
	v_cndmask_b32_e64 v86, v214, v86, s[28:29]
	v_cndmask_b32_e64 v85, v214, v85, s[30:31]
	v_cndmask_b32_e64 v84, v214, v84, s[34:35]
	v_cndmask_b32_e64 v83, v214, v83, s[36:37]
	v_cndmask_b32_e64 v82, v214, v82, s[38:39]
	v_cndmask_b32_e64 v81, v214, v81, s[40:41]
	v_cndmask_b32_e64 v80, v214, v80, s[42:43]
	v_cndmask_b32_e64 v79, v214, v79, s[10:11]
	v_cndmask_b32_e64 v78, v214, v78, s[44:45]
	v_cndmask_b32_e64 v77, v214, v77, s[46:47]
	v_cndmask_b32_e64 v76, v214, v76, s[48:49]
	v_cndmask_b32_e64 v75, v214, v75, s[50:51]
	v_cndmask_b32_e64 v74, v214, v74, s[52:53]
	v_cndmask_b32_e64 v73, v214, v73, s[54:55]
	v_cndmask_b32_e64 v72, v214, v72, s[56:57]
	v_cndmask_b32_e64 v71, v214, v71, s[58:59]
	v_cndmask_b32_e64 v70, v214, v70, s[60:61]
	v_cndmask_b32_e64 v69, v214, v69, s[62:63]
	v_cndmask_b32_e64 v68, v214, v68, s[64:65]
	v_cndmask_b32_e64 v67, v214, v67, s[66:67]
	v_cndmask_b32_e64 v66, v214, v66, s[68:69]
	v_cndmask_b32_e64 v65, v214, v65, s[70:71]
	v_cndmask_b32_e64 v64, v214, v64, s[72:73]

; #define MFMA(a, b, c) __builtin_amdgcn_mfma_f32_32x32x16_bf16((a), (b), (c), 0, 0, 0)
; DI void softmax_pv(f32x16 (&sa)[2], f32x16 (&O)[4], float& m, float& l, const char* sV, int lr, int lh, bool first) {
;     ...
;   float rsum0 = 0.f, rsum1 = 0.f;
; #pragma unroll
;   for (int i = 0; i < 16; ++i) {
;     float p0 = __builtin_amdgcn_exp2f(sa[0][i]);
;     float p1 = __builtin_amdgcn_exp2f(sa[1][i]);
;     sa[0][i] = p0;
;     sa[1][i] = p1;
;     rsum0 += p0;
;     rsum1 += p1;
;   }
;   l += rsum0 + rsum1;
;   bf16x8 pf[4];
; #pragma unroll
;   for (int g4 = 0; g4 < 4; ++g4) {
;     const int kb = g4 >> 1, s2 = g4 & 1;
;     u32x4 pp;
; #pragma unroll
;     for (int j = 0; j < 4; ++j) pp[j] = pk2(sa[kb][8 * s2 + 2 * j], sa[kb][8 * s2 + 2 * j + 1]);
;     pf[g4] = __builtin_bit_cast(bf16x8, pp);
;   }
;   const char* vrd = sV + lr * 144 + lh * 16;
;   bf16x8 vfr[4];
; #pragma unroll
;   for (int t = 0; t < 3; ++t) vfr[t] = *(const bf16x8*)(vrd + (t & 3) * (32 * 144) + (t >> 2) * 32);
;   __builtin_amdgcn_sched_group_barrier(0x100, 3, 0);
; #pragma unroll
;   for (int t = 0; t < 16; ++t) {
;     if (t + 3 < 16) {
;       vfr[(t + 3) & 3] = *(const bf16x8*)(vrd + ((t + 3) & 3) * (32 * 144) + ((t + 3) >> 2) * 32);
;       __builtin_amdgcn_sched_group_barrier(0x100, 1, 0);
;     }
;     O[t & 3] = MFMA(vfr[t & 3], pf[t >> 2], O[t & 3]);
;     __builtin_amdgcn_sched_group_barrier(0x008, 1, 0);
;   }
; DI void mla_item(const Params& p, const GroupP& g, int item, char* smem, bool dry) {
;     ...
;     softmax_pv(sa, O, m, l, sV, lr, lh, kt == 0);
;     __syncthreads();
;     if (more) store_vtile(rv, sV_st);
;   }
.LBB0_233:
	ds_read_b128 v[206:209], v225 offset:25600
	ds_read_b128 v[238:241], v225 offset:30208
	ds_read_b128 v[242:245], v225 offset:34816
	ds_read_b128 v[246:249], v225 offset:39424
	v_exp_f32_e32 v80, v80
	v_exp_f32_e32 v81, v81
	v_exp_f32_e32 v82, v82
	v_exp_f32_e32 v83, v83
	v_exp_f32_e32 v84, v84
	v_exp_f32_e32 v85, v85
	v_exp_f32_e32 v86, v86
	v_exp_f32_e32 v87, v87
	v_cvt_pk_bf16_f32 v234, v80, v81
	v_cvt_pk_bf16_f32 v235, v82, v83
	v_cvt_pk_bf16_f32 v236, v84, v85
	v_cvt_pk_bf16_f32 v237, v86, v87
	v_exp_f32_e32 v232, v88
	v_exp_f32_e32 v231, v89
	s_waitcnt lgkmcnt(3)
	v_mfma_f32_32x32x16_bf16 v[48:63], v[206:209], v[234:237], v[48:63]
	ds_read_b128 v[206:209], v225 offset:25632
	v_exp_f32_e32 v184, v90
	v_exp_f32_e32 v90, v91
	v_exp_f32_e32 v89, v92
	v_exp_f32_e32 v88, v93
	v_exp_f32_e32 v92, v94
	v_exp_f32_e32 v91, v95
	s_waitcnt lgkmcnt(3)
	v_mfma_f32_32x32x16_bf16 v[32:47], v[238:241], v[234:237], v[32:47]
	ds_read_b128 v[238:241], v225 offset:30240
	v_exp_f32_e32 v95, v64
	v_exp_f32_e32 v94, v65
	v_exp_f32_e32 v93, v66
	v_exp_f32_e32 v66, v67
	v_exp_f32_e32 v65, v68
	v_exp_f32_e32 v64, v69
	s_waitcnt lgkmcnt(3)
	v_mfma_f32_32x32x16_bf16 v[16:31], v[242:245], v[234:237], v[16:31]
	ds_read_b128 v[242:245], v225 offset:34848
	v_exp_f32_e32 v68, v70
	v_exp_f32_e32 v67, v71
	v_exp_f32_e32 v233, v73
	v_exp_f32_e32 v71, v75
	v_exp_f32_e32 v70, v76
	v_exp_f32_e32 v69, v77
	s_waitcnt lgkmcnt(3)
	v_mfma_f32_32x32x16_bf16 v[0:15], v[246:249], v[234:237], v[0:15]
	ds_read_b128 v[246:249], v225 offset:39456
	v_cvt_pk_bf16_f32 v234, v232, v231
	v_cvt_pk_bf16_f32 v235, v184, v90
	v_cvt_pk_bf16_f32 v236, v89, v88
	v_cvt_pk_bf16_f32 v237, v92, v91
	v_exp_f32_e32 v73, v79
	s_and_b64 vcc, exec, s[74:75]
	s_waitcnt lgkmcnt(3)
	v_mfma_f32_32x32x16_bf16 v[48:63], v[206:209], v[234:237], v[48:63]
	ds_read_b128 v[206:209], v225 offset:25664
	s_waitcnt lgkmcnt(3)
	v_mfma_f32_32x32x16_bf16 v[32:47], v[238:241], v[234:237], v[32:47]
	ds_read_b128 v[238:241], v225 offset:30272
	s_waitcnt lgkmcnt(3)
	v_mfma_f32_32x32x16_bf16 v[16:31], v[242:245], v[234:237], v[16:31]
	ds_read_b128 v[242:245], v225 offset:34880
	s_waitcnt lgkmcnt(3)
	v_mfma_f32_32x32x16_bf16 v[0:15], v[246:249], v[234:237], v[0:15]
	ds_read_b128 v[202:205], v225 offset:39488
	v_cvt_pk_bf16_f32 v246, v95, v94
	v_cvt_pk_bf16_f32 v247, v93, v66
	v_cvt_pk_bf16_f32 v248, v65, v64
	v_cvt_pk_bf16_f32 v249, v68, v67
	v_exp_f32_e32 v234, v72
	v_exp_f32_e32 v72, v74
	s_waitcnt lgkmcnt(3)
	v_mfma_f32_32x32x16_bf16 v[48:63], v[206:209], v[246:249], v[48:63]
	ds_read_b128 v[206:209], v225 offset:25696
	v_exp_f32_e32 v74, v78
	v_cvt_pk_bf16_f32 v76, v234, v233
	v_cvt_pk_bf16_f32 v77, v72, v71
	v_cvt_pk_bf16_f32 v78, v70, v69
	v_cvt_pk_bf16_f32 v79, v74, v73
	s_waitcnt lgkmcnt(3)
	v_mfma_f32_32x32x16_bf16 v[32:47], v[238:241], v[246:249], v[32:47]
	ds_read_b128 v[236:239], v225 offset:30304
	s_waitcnt lgkmcnt(3)
	v_mfma_f32_32x32x16_bf16 v[16:31], v[242:245], v[246:249], v[16:31]
	ds_read_b128 v[240:243], v225 offset:34912
	s_waitcnt lgkmcnt(3)
	v_mfma_f32_32x32x16_bf16 v[0:15], v[202:205], v[246:249], v[0:15]
	ds_read_b128 v[202:205], v225 offset:39520
	s_waitcnt lgkmcnt(0)
	s_barrier
	v_mfma_f32_32x32x16_bf16 v[48:63], v[206:209], v[76:79], v[48:63]
	v_mfma_f32_32x32x16_bf16 v[32:47], v[236:239], v[76:79], v[32:47]
	v_mfma_f32_32x32x16_bf16 v[16:31], v[240:243], v[76:79], v[16:31]
	v_mfma_f32_32x32x16_bf16 v[0:15], v[202:205], v[76:79], v[0:15]
	s_branch .LBB0_224

; __global__ void __launch_bounds__(NTHR, 2) mega(Params p_unused, int ph_lo, int ph_hi) {
;   __shared__ __attribute__((aligned(16))) char smem[SMEM_BYTES];
	.amdhsa_kernel _Z4mega6Paramsii
		.amdhsa_group_segment_fixed_size 56336
		.amdhsa_private_segment_fixed_size 0
		.amdhsa_kernarg_size 1024
		.amdhsa_user_sgpr_count 2
		.amdhsa_user_sgpr_dispatch_ptr 0
		.amdhsa_user_sgpr_queue_ptr 0
		.amdhsa_user_sgpr_kernarg_segment_ptr 1
		.amdhsa_user_sgpr_dispatch_id 0
		.amdhsa_user_sgpr_kernarg_preload_length 0
		.amdhsa_user_sgpr_kernarg_preload_offset 0
		.amdhsa_user_sgpr_private_segment_size 0
		.amdhsa_uses_dynamic_stack 0
		.amdhsa_enable_private_segment 0
		.amdhsa_system_sgpr_workgroup_id_x 1
		.amdhsa_system_sgpr_workgroup_id_y 0
		.amdhsa_system_sgpr_workgroup_id_z 0
		.amdhsa_system_sgpr_workgroup_info 0
		.amdhsa_system_vgpr_workitem_id 2
		.amdhsa_next_free_vgpr 256
		.amdhsa_next_free_sgpr 102
		.amdhsa_accum_offset 256
		.amdhsa_reserve_vcc 1
		.amdhsa_float_round_mode_32 0
		.amdhsa_float_round_mode_16_64 0
		.amdhsa_float_denorm_mode_32 3
		.amdhsa_float_denorm_mode_16_64 3
		.amdhsa_dx10_clamp 1
		.amdhsa_ieee_mode 1
		.amdhsa_fp16_overflow 0
		.amdhsa_tg_split 0
		.amdhsa_exception_fp_ieee_invalid_op 0
		.amdhsa_exception_fp_denorm_src 0
		.amdhsa_exception_fp_ieee_div_zero 0
		.amdhsa_exception_fp_ieee_overflow 0
		.amdhsa_exception_fp_ieee_underflow 0
		.amdhsa_exception_fp_ieee_inexact 0
		.amdhsa_exception_int_div_zero 0
	.end_amdhsa_kernel

; __global__ void __launch_bounds__(NTHR, 2) mega(Params p_unused, int ph_lo, int ph_hi) {
;   __shared__ __attribute__((aligned(16))) char smem[SMEM_BYTES];
amdhsa.kernels:
  - .agpr_count:     0
    .args:
      - .offset:         0
        .size:           760
        .value_kind:     by_value
      - .offset:         760
        .size:           4
        .value_kind:     by_value
      - .offset:         764
        .size:           4
        .value_kind:     by_value
      - .offset:         768
        .size:           4
        .value_kind:     hidden_block_count_x
      - .offset:         772
        .size:           4
        .value_kind:     hidden_block_count_y
      - .offset:         776
        .size:           4
        .value_kind:     hidden_block_count_z
      - .offset:         780
        .size:           2
        .value_kind:     hidden_group_size_x
      - .offset:         782
        .size:           2
        .value_kind:     hidden_group_size_y
      - .offset:         784
        .size:           2
        .value_kind:     hidden_group_size_z
      - .offset:         786
        .size:           2
        .value_kind:     hidden_remainder_x
      - .offset:         788
        .size:           2
        .value_kind:     hidden_remainder_y
      - .offset:         790
        .size:           2
        .value_kind:     hidden_remainder_z
      - .offset:         808
        .size:           8
        .value_kind:     hidden_global_offset_x
      - .offset:         816
        .size:           8
        .value_kind:     hidden_global_offset_y
      - .offset:         824
        .size:           8
        .value_kind:     hidden_global_offset_z
      - .offset:         832
        .size:           2
        .value_kind:     hidden_grid_dims
      - .offset:         856
        .size:           8
        .value_kind:     hidden_multigrid_sync_arg
    .group_segment_fixed_size: 56336
    .kernarg_segment_align: 8
    .kernarg_segment_size: 1024
    .language:       OpenCL C
    .language_version:
      - 2
      - 0
    .max_flat_workgroup_size: 256
    .name:           _Z4mega6Paramsii
    .private_segment_fixed_size: 0
    .sgpr_count:     108
    .sgpr_spill_count: 506
    .symbol:         _Z4mega6Paramsii.kd
    .uniform_work_group_size: 1
    .uses_dynamic_stack: false
    .vgpr_count:     256
    .vgpr_spill_count: 0
    .wavefront_size: 64
